# P0 row loop: x rows loaded two iterations ahead (two landing register sets, loop unrolled x2, counted waits re-derived)
# baseline (speedup 1.0000x reference)
; #define GAS __attribute__((address_space(1)))
; #define LAS __attribute__((address_space(3)))
; __global__ void __launch_bounds__(NWAVES * 64, 2) fwd(Args args) {
;     ...
;         f32x4 wreg[8][4];
; #pragma unroll
;         for (int c = 0; c < 8; ++c)
; #pragma unroll
;             for (int j = 0; j < 4; ++j) wreg[c][j] = *(const LAS f32x4*)(w8 + c * 1024 + 256 * j + 4 * lane);
;         f32x4 vn[4];
;         if (gw < M) { const GAS f32x4* xr0 = (const GAS f32x4*)(x + (size_t)gw * D) + 2 * lane;
; #pragma unroll
;             for (int j = 0; j < 4; ++j) vn[j] = xr0[128 * (j >> 1) + (j & 1)]; }
;         for (int m = gw; m < M; m += NGW) {
;             f32x4 v[4];
; #pragma unroll
;             for (int j = 0; j < 4; ++j) v[j] = vn[j];
;             if (m + NGW < M) { const GAS f32x4* xr = (const GAS f32x4*)(x + (size_t)(m + NGW) * D) + 2 * lane;
; #pragma unroll
;                 for (int j = 0; j < 4; ++j) vn[j] = xr[128 * (j >> 1) + (j & 1)]; }
;             asm volatile("" :: "v"(v[0]), "v"(v[1]), "v"(v[2]), "v"(v[3]) : "memory");
.LBB0_50:
	s_or_b64 exec, exec, s[6:7]
	s_cmpk_lt_i32 s40, 0x4000
	s_waitcnt lgkmcnt(0)
	s_barrier
	s_cbranch_scc0 .LBB0_65
	s_ashr_i32 s41, s40, 31
	s_lshl_b64 s[6:7], s[40:41], 12
	s_add_u32 s8, s16, s6
	s_addc_u32 s9, s17, s7
	v_lshlrev_b32_e32 v38, 5, v234
	global_load_dwordx4 v[146:149], v38, s[8:9] nt
	global_load_dwordx4 v[154:157], v38, s[8:9] offset:16 nt
	global_load_dwordx4 v[150:153], v38, s[8:9] offset:2048 nt
	global_load_dwordx4 v[158:161], v38, s[8:9] offset:2064 nt
	v_mov_b32_e32 v39, 0
	v_lshl_add_u64 v[162:163], s[16:17], 0, v[38:39]
	s_lshl_b64 s[16:17], s[40:41], 5
	s_add_u32 s16, s60, s16
	v_mov_b32_e32 v35, v39
	s_addc_u32 s17, s61, s17
	v_lshl_add_u64 v[34:35], s[16:17], 0, v[34:35]
	s_mov_b64 s[16:17], 0x100000
	s_ashr_i32 s43, s42, 31
	v_and_b32_e32 v1, 32, v0
	v_lshl_add_u64 v[168:169], v[34:35], 0, s[16:17]
	s_lshl_b64 s[16:17], s[42:43], 5
	s_lshl_b64 s[20:21], s[40:41], 11
	v_cmp_eq_u32_e64 s[6:7], 0, v1
	v_and_b32_e32 v1, 16, v0
	s_add_u32 s20, s60, s20
	v_lshlrev_b32_e32 v36, 4, v234
	v_cmp_eq_u32_e64 s[8:9], 0, v1
	v_and_b32_e32 v1, 8, v0
	v_mov_b32_e32 v37, v39
	s_addc_u32 s21, s61, s21
	v_cmp_eq_u32_e64 s[10:11], 0, v1
	v_add_u32_e32 v2, -4, v8
	v_mov_b32_e32 v3, v39
	v_add_u32_e32 v1, 0, v36
	v_lshl_add_u64 v[34:35], s[20:21], 0, v[36:37]
	s_mov_b64 s[20:21], 0x4000400
	v_lshlrev_b64 v[2:3], 2, v[2:3]
	v_add_u32_e32 v126, 0x12000, v1
	v_lshl_add_u64 v[170:171], v[34:35], 0, s[20:21]
	v_cmp_eq_u32_e64 s[12:13], 0, v4
	v_lshl_add_u64 v[164:165], s[28:29], 0, v[2:3]
	v_lshl_add_u64 v[166:167], s[26:27], 0, v[2:3]
	ds_read_b128 v[2:5], v126 offset:31744
	ds_read_b128 v[6:9], v126 offset:30720
	ds_read_b128 v[10:13], v126 offset:29696
	ds_read_b128 v[14:17], v126 offset:28672
	ds_read_b128 v[18:21], v126 offset:27648
	ds_read_b128 v[22:25], v126 offset:26624
	ds_read_b128 v[26:29], v126 offset:25600
	ds_read_b128 v[30:33], v126 offset:24576
	ds_read_b128 v[34:37], v126 offset:23552
	ds_read_b128 v[38:41], v126 offset:22528
	ds_read_b128 v[42:45], v126 offset:21504
	ds_read_b128 v[46:49], v126 offset:20480
	ds_read_b128 v[50:53], v126 offset:19456
	ds_read_b128 v[54:57], v126 offset:18432
	ds_read_b128 v[58:61], v126 offset:17408
	ds_read_b128 v[62:65], v126 offset:16384
	ds_read_b128 v[66:69], v126 offset:15360
	ds_read_b128 v[70:73], v126 offset:14336
	ds_read_b128 v[74:77], v126 offset:13312
	ds_read_b128 v[78:81], v126 offset:12288
	ds_read_b128 v[82:85], v126 offset:11264
	ds_read_b128 v[86:89], v126 offset:10240
	ds_read_b128 v[90:93], v126 offset:9216
	ds_read_b128 v[94:97], v126 offset:8192
	ds_read_b128 v[98:101], v126 offset:7168
	ds_read_b128 v[102:105], v126 offset:6144
	ds_read_b128 v[106:109], v126 offset:5120
	ds_read_b128 v[110:113], v126 offset:4096
	ds_read_b128 v[114:117], v126 offset:3072
	ds_read_b128 v[118:121], v126 offset:2048
	ds_read_b128 v[122:125], v126 offset:1024
	ds_read_b128 v[126:129], v126
	v_mbcnt_lo_u32_b32 v1, -1, 0
	v_cmp_lt_u32_e64 s[14:15], 31, v234
	s_lshl_b64 s[20:21], s[42:43], 11
	v_mbcnt_hi_u32_b32 v1, -1, v1
	s_mov_b32 s3, 0x41a00000
	s_mov_b32 s4, 0x3fb8aa3b
	s_mov_b32 s33, 0xc2ce8ed0
	s_mov_b32 s35, 0x42b17218
	s_mov_b32 s36, 0x7f800000
	s_mov_b32 s37, 0x3f2aaaab
	v_mov_b32_e32 v174, 0x3ecc95a3
	s_mov_b32 s43, 0x3f317218
	s_mov_b32 s48, 0x33800000
	s_mov_b32 s49, 0xbfb8aa3b
	s_mov_b32 s50, 0x42ce8ed0
	s_mov_b32 s51, 0xc2b17218
	v_mov_b32_e32 v175, 0x7f800000
	v_mov_b32_e32 v172, 0x3f317218
	s_mov_b64 s[44:45], exec
	s_and_b64 exec, exec, s[14:15]
	global_load_dword v241, v[164:165], off
	global_load_dword v242, v[166:167], off
	s_mov_b64 exec, s[44:45]
	s_add_i32 s62, s40, s42
	s_min_i32 s62, s62, 0x3fff
	s_mov_b32 s63, 0
	s_lshl_b64 s[28:29], s[62:63], 12
	v_lshl_add_u64 v[200:201], v[162:163], 0, s[28:29]
	global_load_dwordx4 v[188:191], v[200:201], off nt
	global_load_dwordx4 v[192:195], v[200:201], off offset:16 nt
	global_load_dwordx4 v[196:199], v[200:201], off offset:2048 nt
	s_nop 0
	global_load_dwordx4 v[200:203], v[200:201], off offset:2064 nt
	s_mov_b32 s98, 4
.LrowA_top:
	s_add_i32 s40, s40, s42
	s_add_i32 s62, s40, s42
	s_min_i32 s62, s62, 0x3fff
	s_mov_b32 s63, 0
	s_lshl_b64 s[28:29], s[62:63], 12
	v_lshl_add_u64 v[142:143], v[162:163], 0, s[28:29]
	global_load_dwordx4 v[130:133], v[142:143], off nt
	global_load_dwordx4 v[134:137], v[142:143], off offset:16 nt
	global_load_dwordx4 v[138:141], v[142:143], off offset:2048 nt
	s_nop 0
	global_load_dwordx4 v[142:145], v[142:143], off offset:2064 nt
	s_waitcnt vmcnt(13) lgkmcnt(0)
	v_mul_f32_e32 v173, v147, v127
	v_fmac_f32_e32 v173, v146, v126
	s_waitcnt vmcnt(12)
	v_mul_f32_e32 v176, v155, v123
	v_fmac_f32_e32 v173, v148, v128
	v_fmac_f32_e32 v176, v154, v122
	v_fmac_f32_e32 v173, v149, v129
	v_fmac_f32_e32 v176, v156, v124
	v_add_f32_e32 v173, 0, v173
	v_fmac_f32_e32 v176, v157, v125
	v_add_f32_e32 v173, v173, v176
	s_waitcnt vmcnt(11)
	v_mul_f32_e32 v176, v151, v119
	v_fmac_f32_e32 v176, v150, v118
	v_fmac_f32_e32 v176, v152, v120
	v_fmac_f32_e32 v176, v153, v121
	v_add_f32_e32 v173, v173, v176
	s_waitcnt vmcnt(10)
; __global__ void __launch_bounds__(NWAVES * 64, 2) fwd(Args args) {
;     ...
;             float acc[8];
; #pragma unroll
;             for (int c = 0; c < 8; ++c) { float a = 0.f;
; #pragma unroll
;                 for (int j = 0; j < 4; ++j) { const f32x4 w = wreg[c][j]; a += v[j].x * w.x + v[j].y * w.y + v[j].z * w.z + v[j].w * w.w; }
;                 acc[c] = a; }
;             float a4[4], a2[2], a1;
;             { const bool hi = (lane & 32) != 0;
; #pragma unroll
;               for (int i = 0; i < 4; ++i) { const float send = hi ? acc[i] : acc[4 + i], keep = hi ? acc[4 + i] : acc[i]; a4[i] = keep + __shfl_xor(send, 32); } }
	v_mul_f32_e32 v176, v159, v115
	v_fmac_f32_e32 v176, v158, v114
	v_fmac_f32_e32 v176, v160, v116
	v_fmac_f32_e32 v176, v161, v117
	v_add_f32_e32 v173, v173, v176
	v_mul_f32_e32 v176, v147, v111
	v_fmac_f32_e32 v176, v146, v110
	v_mul_f32_e32 v177, v155, v107
	v_fmac_f32_e32 v176, v148, v112
	v_fmac_f32_e32 v177, v154, v106
	v_fmac_f32_e32 v176, v149, v113
	v_fmac_f32_e32 v177, v156, v108
	v_add_f32_e32 v176, 0, v176
	v_fmac_f32_e32 v177, v157, v109
	v_add_f32_e32 v176, v176, v177
	v_mul_f32_e32 v177, v151, v103
	v_fmac_f32_e32 v177, v150, v102
	v_fmac_f32_e32 v177, v152, v104
	v_fmac_f32_e32 v177, v153, v105
	v_add_f32_e32 v176, v176, v177
	v_mul_f32_e32 v177, v159, v99
	v_fmac_f32_e32 v177, v158, v98
	v_fmac_f32_e32 v177, v160, v100
	v_fmac_f32_e32 v177, v161, v101
	v_add_f32_e32 v176, v176, v177
	v_mul_f32_e32 v177, v147, v95
	v_fmac_f32_e32 v177, v146, v94
	v_mul_f32_e32 v178, v155, v91
	v_fmac_f32_e32 v177, v148, v96
	v_fmac_f32_e32 v178, v154, v90
	v_fmac_f32_e32 v177, v149, v97
	v_fmac_f32_e32 v178, v156, v92
	v_add_f32_e32 v177, 0, v177
	v_fmac_f32_e32 v178, v157, v93
	v_add_f32_e32 v177, v177, v178
	v_mul_f32_e32 v178, v151, v87
	v_fmac_f32_e32 v178, v150, v86
	v_fmac_f32_e32 v178, v152, v88
	v_fmac_f32_e32 v178, v153, v89
	v_add_f32_e32 v177, v177, v178
	v_mul_f32_e32 v178, v159, v83
	v_fmac_f32_e32 v178, v158, v82
	v_fmac_f32_e32 v178, v160, v84
	v_fmac_f32_e32 v178, v161, v85
	v_add_f32_e32 v177, v177, v178
	v_mul_f32_e32 v178, v147, v79
	v_fmac_f32_e32 v178, v146, v78
	v_mul_f32_e32 v179, v155, v75
	v_fmac_f32_e32 v178, v148, v80
	v_fmac_f32_e32 v179, v154, v74
	v_fmac_f32_e32 v178, v149, v81
	v_fmac_f32_e32 v179, v156, v76
	v_add_f32_e32 v178, 0, v178
	v_fmac_f32_e32 v179, v157, v77
	v_add_f32_e32 v178, v178, v179
	v_mul_f32_e32 v179, v151, v71
	v_fmac_f32_e32 v179, v150, v70
	v_fmac_f32_e32 v179, v152, v72
	v_fmac_f32_e32 v179, v153, v73
	v_add_f32_e32 v178, v178, v179
	v_mul_f32_e32 v179, v159, v67
	v_fmac_f32_e32 v179, v158, v66
	v_fmac_f32_e32 v179, v160, v68
	v_fmac_f32_e32 v179, v161, v69
	v_add_f32_e32 v178, v178, v179
	v_mul_f32_e32 v179, v147, v63
	v_fmac_f32_e32 v179, v146, v62
	v_mul_f32_e32 v180, v155, v59
	v_fmac_f32_e32 v179, v148, v64
	v_fmac_f32_e32 v180, v154, v58
	v_fmac_f32_e32 v179, v149, v65
	v_fmac_f32_e32 v180, v156, v60
	v_add_f32_e32 v179, 0, v179
	v_fmac_f32_e32 v180, v157, v61
	v_add_f32_e32 v179, v179, v180
	v_mul_f32_e32 v180, v151, v55
	v_fmac_f32_e32 v180, v150, v54
	v_fmac_f32_e32 v180, v152, v56
	v_fmac_f32_e32 v180, v153, v57
	v_add_f32_e32 v179, v179, v180
	v_mul_f32_e32 v180, v159, v51
	v_fmac_f32_e32 v180, v158, v50
	v_fmac_f32_e32 v180, v160, v52
	v_fmac_f32_e32 v180, v161, v53
	v_add_f32_e32 v179, v179, v180
	v_mul_f32_e32 v180, v147, v47
	v_fmac_f32_e32 v180, v146, v46
	v_mul_f32_e32 v181, v155, v43
	v_fmac_f32_e32 v180, v148, v48
	v_fmac_f32_e32 v181, v154, v42
	v_fmac_f32_e32 v180, v149, v49
	v_fmac_f32_e32 v181, v156, v44
	v_add_f32_e32 v180, 0, v180
	v_fmac_f32_e32 v181, v157, v45
	v_add_f32_e32 v180, v180, v181
	v_mul_f32_e32 v181, v151, v39
	v_fmac_f32_e32 v181, v150, v38
	v_fmac_f32_e32 v181, v152, v40
	v_fmac_f32_e32 v181, v153, v41
	v_add_f32_e32 v180, v180, v181
	v_mul_f32_e32 v181, v159, v35
	v_fmac_f32_e32 v181, v158, v34
	v_fmac_f32_e32 v181, v160, v36
	v_fmac_f32_e32 v181, v161, v37
	v_add_f32_e32 v180, v180, v181
	v_mul_f32_e32 v181, v147, v31
	v_fmac_f32_e32 v181, v146, v30
	v_mul_f32_e32 v182, v155, v27
	v_fmac_f32_e32 v181, v148, v32
	v_fmac_f32_e32 v182, v154, v26
	v_fmac_f32_e32 v181, v149, v33
	v_fmac_f32_e32 v182, v156, v28
	v_add_f32_e32 v181, 0, v181
	v_fmac_f32_e32 v182, v157, v29
	v_add_f32_e32 v181, v181, v182
	v_mul_f32_e32 v182, v151, v23
	v_fmac_f32_e32 v182, v150, v22
	v_fmac_f32_e32 v182, v152, v24
	v_fmac_f32_e32 v182, v153, v25
	v_add_f32_e32 v181, v181, v182
	v_mul_f32_e32 v182, v159, v19
	v_fmac_f32_e32 v182, v158, v18
	v_fmac_f32_e32 v182, v160, v20
	v_fmac_f32_e32 v182, v161, v21
	v_add_f32_e32 v181, v181, v182
	v_mul_f32_e32 v182, v147, v15
	v_fmac_f32_e32 v182, v146, v14
	v_mul_f32_e32 v183, v155, v11
	v_fmac_f32_e32 v182, v148, v16
	v_fmac_f32_e32 v183, v154, v10
	v_fmac_f32_e32 v182, v149, v17
	v_fmac_f32_e32 v183, v156, v12
	v_add_f32_e32 v182, 0, v182
	v_fmac_f32_e32 v183, v157, v13
	v_add_f32_e32 v182, v182, v183
	v_mul_f32_e32 v183, v151, v7
	v_fmac_f32_e32 v183, v150, v6
	v_fmac_f32_e32 v183, v152, v8
	v_fmac_f32_e32 v183, v153, v9
	v_and_b32_e32 v186, 64, v1
	v_add_f32_e32 v182, v182, v183
	v_mul_f32_e32 v183, v159, v3
	v_xor_b32_e32 v185, 32, v1
	v_add_u32_e32 v186, 64, v186
	v_fmac_f32_e32 v183, v158, v2
	v_cmp_lt_i32_e32 vcc, v185, v186
	v_fmac_f32_e32 v183, v160, v4
	v_cndmask_b32_e64 v187, v173, v179, s[6:7]
	v_cndmask_b32_e32 v185, v1, v185, vcc
	v_lshlrev_b32_e32 v185, 2, v185
	v_fmac_f32_e32 v183, v161, v5
	v_cndmask_b32_e64 v173, v179, v173, s[6:7]
	v_cndmask_b32_e64 v179, v176, v180, s[6:7]
	v_add_f32_e32 v182, v182, v183
	ds_bpermute_b32 v179, v185, v179
	v_cndmask_b32_e64 v176, v180, v176, s[6:7]
	v_cndmask_b32_e64 v180, v177, v181, s[6:7]
	v_cndmask_b32_e64 v183, v178, v182, s[6:7]
	ds_bpermute_b32 v187, v185, v187
	ds_bpermute_b32 v180, v185, v180
	ds_bpermute_b32 v183, v185, v183
	s_waitcnt lgkmcnt(3)
	v_add_f32_e32 v176, v176, v179
	v_xor_b32_e32 v179, 16, v1
	v_cndmask_b32_e64 v177, v181, v177, s[6:7]
	v_cndmask_b32_e64 v178, v182, v178, s[6:7]
	v_cmp_lt_i32_e32 vcc, v179, v186
	s_waitcnt lgkmcnt(2)
	v_add_f32_e32 v173, v173, v187
	s_waitcnt lgkmcnt(1)
	v_add_f32_e32 v177, v177, v180
	s_waitcnt lgkmcnt(0)
; #define GAS __attribute__((address_space(1)))
; __device__ __forceinline__ unsigned pk2(float lo, float hi) { const f32x2_t v = {lo, hi}; return __builtin_bit_cast(unsigned, __builtin_convertvector(v, bf16x2_t)); }
; __global__ void __launch_bounds__(NWAVES * 64, 2) fwd(Args args) {
;     ...
;             GAS v4u* o16 = (GAS v4u*)(XB + (size_t)m * D) + lane;
; #pragma unroll
;             for (int jj = 0; jj < 2; ++jj) { v4u o; o.x = pk2(v[2 * jj].x, v[2 * jj].y); o.y = pk2(v[2 * jj].z, v[2 * jj].w); o.z = pk2(v[2 * jj + 1].x, v[2 * jj + 1].y); o.w = pk2(v[2 * jj + 1].z, v[2 * jj + 1].w); o16[64 * jj] = o; }
;             float acc[8];
; #pragma unroll
;             for (int c = 0; c < 8; ++c) { float a = 0.f;
; #pragma unroll
;                 for (int j = 0; j < 4; ++j) { const f32x4 w = wreg[c][j]; a += v[j].x * w.x + v[j].y * w.y + v[j].z * w.z + v[j].w * w.w; }
;                 acc[c] = a; }
;             float a4[4], a2[2], a1;
;             { const bool hi = (lane & 32) != 0;
; #pragma unroll
;               for (int i = 0; i < 4; ++i) { const float send = hi ? acc[i] : acc[4 + i], keep = hi ? acc[4 + i] : acc[i]; a4[i] = keep + __shfl_xor(send, 32); } }
;             { const bool hi = (lane & 16) != 0;
; #pragma unroll
;               for (int i = 0; i < 2; ++i) { const float send = hi ? a4[i] : a4[2 + i], keep = hi ? a4[2 + i] : a4[i]; a2[i] = keep + __shfl_xor(send, 16); } }
;             { const bool hi = (lane & 8) != 0; const float send = hi ? a2[0] : a2[1], keep = hi ? a2[1] : a2[0]; a1 = keep + __shfl_xor(send, 8); }
;             a1 += __shfl_xor(a1, 4); a1 += __shfl_xor(a1, 2); a1 += __shfl_xor(a1, 1);
;             if ((lane & 7) == 0) { const int cc = lane >> 3; float r;
;                 if (cc < 4) r = 1.f / (1.f + expf(-a1));
;                 else { const int h = cc - 4; const float z = a1 + dt_bias[h]; const float sp = z > 20.f ? z : log1pf(expf(z)); r = -expf(A_log[h]) * sp; }
	v_add_f32_e32 v178, v178, v183
	v_cndmask_b32_e32 v179, v1, v179, vcc
	v_lshlrev_b32_e32 v179, 2, v179
	v_cndmask_b32_e64 v180, v173, v177, s[8:9]
	v_cndmask_b32_e64 v181, v176, v178, s[8:9]
	ds_bpermute_b32 v180, v179, v180
	ds_bpermute_b32 v179, v179, v181
	v_cndmask_b32_e64 v176, v178, v176, s[8:9]
	v_xor_b32_e32 v178, 8, v1
	v_cndmask_b32_e64 v173, v177, v173, s[8:9]
	v_cmp_lt_i32_e32 vcc, v178, v186
	s_waitcnt lgkmcnt(1)
	v_add_f32_e32 v173, v173, v180
	s_waitcnt lgkmcnt(0)
	v_add_f32_e32 v176, v176, v179
	v_cndmask_b32_e32 v178, v1, v178, vcc
	v_cndmask_b32_e64 v177, v173, v176, s[10:11]
	v_lshlrev_b32_e32 v178, 2, v178
	ds_bpermute_b32 v177, v178, v177
	v_cndmask_b32_e64 v173, v176, v173, s[10:11]
	v_xor_b32_e32 v176, 4, v1
	v_cmp_lt_i32_e32 vcc, v176, v186
	s_waitcnt lgkmcnt(0)
	v_add_f32_e32 v173, v173, v177
	v_cvt_pk_bf16_f32 v146, v146, v147
	v_cndmask_b32_e32 v176, v1, v176, vcc
	v_lshlrev_b32_e32 v176, 2, v176
	ds_bpermute_b32 v176, v176, v173
	v_cvt_pk_bf16_f32 v147, v148, v149
	v_xor_b32_e32 v148, 2, v1
	v_cmp_lt_i32_e32 vcc, v148, v186
	v_cvt_pk_bf16_f32 v149, v156, v157
	s_waitcnt lgkmcnt(0)
	v_add_f32_e32 v173, v173, v176
	v_cndmask_b32_e32 v148, v1, v148, vcc
	v_lshlrev_b32_e32 v148, 2, v148
	ds_bpermute_b32 v176, v148, v173
	v_cvt_pk_bf16_f32 v148, v154, v155
	global_store_dwordx4 v[170:171], v[146:149], off offset:-1024
	s_nop 1
	v_xor_b32_e32 v147, 1, v1
	v_cmp_lt_i32_e32 vcc, v147, v186
	s_waitcnt lgkmcnt(0)
	v_add_f32_e32 v146, v173, v176
	v_cvt_pk_bf16_f32 v148, v150, v151
	v_cndmask_b32_e32 v147, v1, v147, vcc
	v_lshlrev_b32_e32 v147, 2, v147
	ds_bpermute_b32 v147, v147, v146
	v_cvt_pk_bf16_f32 v149, v152, v153
	v_cvt_pk_bf16_f32 v150, v158, v159
	v_cvt_pk_bf16_f32 v151, v160, v161
	global_store_dwordx4 v[170:171], v[148:151], off
	s_and_saveexec_b64 s[28:29], s[12:13]
	s_cbranch_execz .LrowA_53
	s_waitcnt lgkmcnt(0)
	v_add_f32_e32 v146, v146, v147
	s_and_saveexec_b64 s[44:45], s[14:15]
	s_xor_b64 s[44:45], exec, s[44:45]
	s_cbranch_execz .LrowA_62
	v_add_f32_e32 v146, v146, v241
	v_cmp_nlt_f32_e32 vcc, s3, v146
	s_and_saveexec_b64 s[46:47], vcc
	s_cbranch_execz .LrowA_61
	v_mul_f32_e32 v147, 0x3fb8aa3b, v146
	v_rndne_f32_e32 v148, v147
	v_sub_f32_e32 v149, v147, v148
	v_fma_f32 v147, v146, s4, -v147
	v_fmac_f32_e32 v147, 0x32a5705f, v146
	v_add_f32_e32 v147, v149, v147
	v_cvt_i32_f32_e32 v148, v148
	v_exp_f32_e32 v147, v147
	v_cmp_ngt_f32_e32 vcc, s33, v146
	v_ldexp_f32 v147, v147, v148
	s_nop 0
	v_cndmask_b32_e32 v147, 0, v147, vcc
	v_cmp_nlt_f32_e32 vcc, s35, v146
	s_nop 1
	v_cndmask_b32_e32 v160, v175, v147, vcc
	v_add_f32_e32 v148, 1.0, v160
	v_add_f32_e32 v146, -1.0, v148
	v_sub_f32_e32 v147, v146, v148
	v_add_f32_e32 v147, 1.0, v147
	v_sub_f32_e32 v146, v160, v146
	v_add_f32_e32 v149, v146, v147
	v_frexp_mant_f32_e32 v150, v148
	v_cvt_f64_f32_e32 v[146:147], v148
	v_frexp_exp_i32_f64_e32 v146, v[146:147]
	v_cmp_gt_f32_e32 vcc, s37, v150
	s_nop 1
	v_subbrev_co_u32_e32 v154, vcc, 0, v146, vcc
	v_sub_u32_e32 v146, 0, v154
	v_ldexp_f32 v147, v148, v146
	v_add_f32_e32 v148, -1.0, v147
	v_add_f32_e32 v150, 1.0, v147
	v_ldexp_f32 v146, v149, v146
	v_add_f32_e32 v149, 1.0, v148
	v_add_f32_e32 v151, -1.0, v150
	v_sub_f32_e32 v149, v147, v149
	v_sub_f32_e32 v147, v147, v151
	v_add_f32_e32 v149, v146, v149
	v_add_f32_e32 v146, v146, v147
	v_add_f32_e32 v155, v150, v146
	v_rcp_f32_e32 v157, v155
	v_sub_f32_e32 v147, v150, v155
	v_add_f32_e32 v156, v146, v147
	v_add_f32_e32 v147, v148, v149
	v_mul_f32_e32 v159, v147, v157
	v_sub_f32_e32 v146, v148, v147
	v_mul_f32_e32 v148, v155, v159
	v_fma_f32 v150, v159, v155, -v148
	v_fmac_f32_e32 v150, v159, v156
	v_add_f32_e32 v158, v149, v146
	v_add_f32_e32 v146, v148, v150
	v_sub_f32_e32 v149, v147, v146
	v_pk_add_f32 v[152:153], v[146:147], v[148:149] neg_lo:[0,1] neg_hi:[0,1]
	v_mov_b32_e32 v151, v146
	v_pk_add_f32 v[146:147], v[152:153], v[150:151] neg_lo:[0,1] neg_hi:[0,1]
	v_cmp_neq_f32_e32 vcc, s36, v160
	v_add_f32_e32 v147, v158, v147
	v_add_f32_e32 v146, v146, v147
	v_add_f32_e32 v147, v149, v146
	v_mul_f32_e32 v158, v157, v147
	v_mul_f32_e32 v148, v155, v158
	v_fma_f32 v150, v158, v155, -v148
	v_fmac_f32_e32 v150, v158, v156
	v_sub_f32_e32 v149, v149, v147
	v_add_f32_e32 v155, v146, v149
	v_add_f32_e32 v146, v148, v150
	v_sub_f32_e32 v149, v147, v146
	v_pk_add_f32 v[152:153], v[146:147], v[148:149] neg_lo:[0,1] neg_hi:[0,1]
	v_mov_b32_e32 v151, v146
	v_pk_add_f32 v[146:147], v[152:153], v[150:151] neg_lo:[0,1] neg_hi:[0,1]
	s_nop 0
	v_add_f32_e32 v147, v155, v147
	v_add_f32_e32 v146, v146, v147
	v_add_f32_e32 v147, v159, v158
	v_add_f32_e32 v146, v149, v146
	v_sub_f32_e32 v148, v147, v159
	v_mul_f32_e32 v146, v157, v146
	v_sub_f32_e32 v148, v158, v148
	v_add_f32_e32 v148, v148, v146
	v_add_f32_e32 v150, v147, v148
	v_mul_f32_e32 v151, v150, v150
	v_fmamk_f32 v146, v151, 0x3e9b6dac, v174
	v_fmaak_f32 v173, v151, v146, 0x3f2aaada
	v_cvt_f32_i32_e32 v146, v154
	v_sub_f32_e32 v147, v150, v147
	v_sub_f32_e32 v147, v148, v147
	v_ldexp_f32 v152, v147, 1
	v_mul_f32_e32 v147, v150, v151
	v_ldexp_f32 v149, v150, 1
	v_pk_mul_f32 v[150:151], v[146:147], v[172:173]
	s_nop 0
	v_fma_f32 v148, v146, s43, -v150
	v_fmac_f32_e32 v148, 0xb102e308, v146
	v_pk_add_f32 v[146:147], v[150:151], v[148:149]
	s_nop 0
	v_sub_f32_e32 v149, v147, v149
	v_sub_f32_e32 v149, v151, v149
	v_add_f32_e32 v153, v152, v149
	v_mov_b32_e32 v152, v150
	v_pk_add_f32 v[150:151], v[146:147], v[150:151] neg_lo:[0,1] neg_hi:[0,1]
	v_pk_add_f32 v[154:155], v[146:147], v[152:153]
	v_mov_b32_e32 v149, v146
	v_mov_b32_e32 v151, v155
	v_pk_add_f32 v[156:157], v[148:149], v[150:151] neg_lo:[0,1] neg_hi:[0,1]
	v_pk_add_f32 v[148:149], v[148:149], v[150:151]
	v_mov_b32_e32 v152, v153
	v_pk_add_f32 v[150:151], v[148:149], v[146:147] op_sel:[1,0] op_sel_hi:[0,1] neg_lo:[0,1] neg_hi:[0,1]
	v_pk_add_f32 v[158:159], v[154:155], v[150:151] op_sel_hi:[1,0] neg_lo:[0,1] neg_hi:[0,1]
	v_mov_b32_e32 v154, v155
	v_mov_b32_e32 v155, v149
	v_pk_mov_b32 v[150:151], v[146:147], v[150:151] op_sel:[1,0]
	v_mov_b32_e32 v153, v146
	v_pk_add_f32 v[150:151], v[154:155], v[150:151] neg_lo:[0,1] neg_hi:[0,1]
	v_mov_b32_e32 v158, v156
	v_pk_add_f32 v[146:147], v[152:153], v[150:151] neg_lo:[0,1] neg_hi:[0,1]
	v_mov_b32_e32 v157, v149
	v_pk_add_f32 v[150:151], v[158:159], v[146:147]
	s_nop 0
	v_pk_add_f32 v[152:153], v[150:151], v[150:151] op_sel:[0,1] op_sel_hi:[1,0]
	s_nop 0
	v_pk_add_f32 v[148:149], v[148:149], v[152:153] op_sel:[1,0] op_sel_hi:[0,1]
	v_mov_b32_e32 v151, v148
	v_pk_add_f32 v[154:155], v[150:151], v[156:157] neg_lo:[0,1] neg_hi:[0,1]
	v_mov_b32_e32 v147, v152
	v_sub_f32_e32 v149, v150, v154
	v_pk_add_f32 v[146:147], v[146:147], v[154:155] neg_lo:[0,1] neg_hi:[0,1]
	v_sub_f32_e32 v149, v156, v149
	v_add_f32_e32 v146, v146, v149
	v_add_f32_e32 v146, v146, v147
	v_add_f32_e32 v146, v148, v146
	v_cndmask_b32_e32 v146, v175, v146, vcc
	v_cmp_lt_f32_e64 vcc, |v160|, s48
	s_nop 1
	v_cndmask_b32_e32 v146, v146, v160, vcc

; #define GAS __attribute__((address_space(1)))
; __device__ __forceinline__ unsigned pk2(float lo, float hi) { const f32x2_t v = {lo, hi}; return __builtin_bit_cast(unsigned, __builtin_convertvector(v, bf16x2_t)); }
; __global__ void __launch_bounds__(NWAVES * 64, 2) fwd(Args args) {
;     ...
;         for (int m = gw; m < M; m += NGW) {
;             f32x4 v[4];
; #pragma unroll
;             for (int j = 0; j < 4; ++j) v[j] = vn[j];
;             if (m + NGW < M) { const GAS f32x4* xr = (const GAS f32x4*)(x + (size_t)(m + NGW) * D) + 2 * lane;
; #pragma unroll
;                 for (int j = 0; j < 4; ++j) vn[j] = xr[128 * (j >> 1) + (j & 1)]; }
;             asm volatile("" :: "v"(v[0]), "v"(v[1]), "v"(v[2]), "v"(v[3]) : "memory");
;             GAS v4u* o16 = (GAS v4u*)(XB + (size_t)m * D) + lane;
; #pragma unroll
;             for (int jj = 0; jj < 2; ++jj) { v4u o; o.x = pk2(v[2 * jj].x, v[2 * jj].y); o.y = pk2(v[2 * jj].z, v[2 * jj].w); o.z = pk2(v[2 * jj + 1].x, v[2 * jj + 1].y); o.w = pk2(v[2 * jj + 1].z, v[2 * jj + 1].w); o16[64 * jj] = o; }
;             float acc[8];
; #pragma unroll
;             for (int c = 0; c < 8; ++c) { float a = 0.f;
; #pragma unroll
;                 for (int j = 0; j < 4; ++j) { const f32x4 w = wreg[c][j]; a += v[j].x * w.x + v[j].y * w.y + v[j].z * w.z + v[j].w * w.w; }
;                 acc[c] = a; }
;     ...
;             if ((lane & 7) == 0) { const int cc = lane >> 3; float r;
;                 if (cc < 4) r = 1.f / (1.f + expf(-a1));
;                 else { const int h = cc - 4; const float z = a1 + dt_bias[h]; const float sp = z > 20.f ? z : log1pf(expf(z)); r = -expf(A_log[h]) * sp; }
;                 GBT[(size_t)m * 8 + cc] = r;
.LrowA_62:
	s_andn2_saveexec_b64 s[44:45], s[44:45]
	s_cbranch_execz .LrowA_52
	v_mul_f32_e32 v147, 0xbfb8aa3b, v146
	v_rndne_f32_e32 v148, v147
	v_sub_f32_e32 v149, v147, v148
	v_fma_f32 v147, v146, s49, -v147
	v_fmac_f32_e32 v147, 0xb2a5705f, v146
	v_add_f32_e32 v147, v149, v147
	v_cvt_i32_f32_e32 v148, v148
	v_exp_f32_e32 v147, v147
	v_cmp_nlt_f32_e32 vcc, s50, v146
	v_ldexp_f32 v147, v147, v148
	s_nop 0
	v_cndmask_b32_e32 v147, 0, v147, vcc
	v_cmp_ngt_f32_e32 vcc, s51, v146
	s_nop 1
	v_cndmask_b32_e32 v146, v175, v147, vcc
	v_add_f32_e32 v146, 1.0, v146
	v_div_scale_f32 v147, s[46:47], v146, v146, 1.0
	v_rcp_f32_e32 v148, v147
	s_nop 0
	v_fma_f32 v149, -v147, v148, 1.0
	v_fmac_f32_e32 v148, v149, v148
	v_div_scale_f32 v149, vcc, 1.0, v146, 1.0
	v_mul_f32_e32 v150, v149, v148
	v_fma_f32 v151, -v147, v150, v149
	v_fmac_f32_e32 v150, v151, v148
	v_fma_f32 v147, -v147, v150, v149
	v_div_fmas_f32 v147, v147, v148, v150
	v_div_fixup_f32 v147, v147, v146, 1.0
	s_branch .LrowA_52
.LrowA_52:
	s_or_b64 exec, exec, s[44:45]
	global_store_dword v[168:169], v147, off
.LrowA_53:
	s_or_b64 exec, exec, s[28:29]
	v_lshl_add_u64 v[168:169], v[168:169], 0, s[16:17]
	v_lshl_add_u64 v[170:171], v[170:171], 0, s[20:21]
	s_waitcnt vmcnt(7) lgkmcnt(0)
	v_mov_b32_e32 v146, v188
	v_mov_b32_e32 v147, v189
	v_mov_b32_e32 v148, v190
	v_mov_b32_e32 v149, v191
	v_mov_b32_e32 v154, v192
	v_mov_b32_e32 v155, v193
	v_mov_b32_e32 v156, v194
	v_mov_b32_e32 v157, v195
	v_mov_b32_e32 v150, v196
	v_mov_b32_e32 v151, v197
	v_mov_b32_e32 v152, v198
	v_mov_b32_e32 v153, v199
	v_mov_b32_e32 v158, v200
	v_mov_b32_e32 v159, v201
	v_mov_b32_e32 v160, v202
	v_mov_b32_e32 v161, v203
.LrowB_top:
	s_add_i32 s40, s40, s42
	s_add_i32 s62, s40, s42
	s_min_i32 s62, s62, 0x3fff
	s_mov_b32 s63, 0
	s_lshl_b64 s[28:29], s[62:63], 12
	v_lshl_add_u64 v[200:201], v[162:163], 0, s[28:29]
	global_load_dwordx4 v[188:191], v[200:201], off nt
	global_load_dwordx4 v[192:195], v[200:201], off offset:16 nt
	global_load_dwordx4 v[196:199], v[200:201], off offset:2048 nt
	s_nop 0
	global_load_dwordx4 v[200:203], v[200:201], off offset:2064 nt
	s_waitcnt vmcnt(13) lgkmcnt(0)
	v_mul_f32_e32 v173, v147, v127
	v_fmac_f32_e32 v173, v146, v126
	s_waitcnt vmcnt(12)
	v_mul_f32_e32 v176, v155, v123
	v_fmac_f32_e32 v173, v148, v128
	v_fmac_f32_e32 v176, v154, v122
	v_fmac_f32_e32 v173, v149, v129
	v_fmac_f32_e32 v176, v156, v124
	v_add_f32_e32 v173, 0, v173
	v_fmac_f32_e32 v176, v157, v125
	v_add_f32_e32 v173, v173, v176
	s_waitcnt vmcnt(11)
	v_mul_f32_e32 v176, v151, v119
	v_fmac_f32_e32 v176, v150, v118
	v_fmac_f32_e32 v176, v152, v120
	v_fmac_f32_e32 v176, v153, v121
	v_add_f32_e32 v173, v173, v176
	s_waitcnt vmcnt(10)
	v_mul_f32_e32 v176, v159, v115
	v_fmac_f32_e32 v176, v158, v114
	v_fmac_f32_e32 v176, v160, v116
	v_fmac_f32_e32 v176, v161, v117
	v_add_f32_e32 v173, v173, v176
	v_mul_f32_e32 v176, v147, v111
	v_fmac_f32_e32 v176, v146, v110
	v_mul_f32_e32 v177, v155, v107
	v_fmac_f32_e32 v176, v148, v112
	v_fmac_f32_e32 v177, v154, v106
	v_fmac_f32_e32 v176, v149, v113
	v_fmac_f32_e32 v177, v156, v108
	v_add_f32_e32 v176, 0, v176
	v_fmac_f32_e32 v177, v157, v109
	v_add_f32_e32 v176, v176, v177
	v_mul_f32_e32 v177, v151, v103
	v_fmac_f32_e32 v177, v150, v102
	v_fmac_f32_e32 v177, v152, v104
	v_fmac_f32_e32 v177, v153, v105
	v_add_f32_e32 v176, v176, v177
	v_mul_f32_e32 v177, v159, v99
	v_fmac_f32_e32 v177, v158, v98
	v_fmac_f32_e32 v177, v160, v100
	v_fmac_f32_e32 v177, v161, v101
	v_add_f32_e32 v176, v176, v177
	v_mul_f32_e32 v177, v147, v95
	v_fmac_f32_e32 v177, v146, v94
	v_mul_f32_e32 v178, v155, v91
	v_fmac_f32_e32 v177, v148, v96
	v_fmac_f32_e32 v178, v154, v90
	v_fmac_f32_e32 v177, v149, v97
	v_fmac_f32_e32 v178, v156, v92
	v_add_f32_e32 v177, 0, v177
	v_fmac_f32_e32 v178, v157, v93
	v_add_f32_e32 v177, v177, v178
	v_mul_f32_e32 v178, v151, v87
	v_fmac_f32_e32 v178, v150, v86
	v_fmac_f32_e32 v178, v152, v88
	v_fmac_f32_e32 v178, v153, v89
	v_add_f32_e32 v177, v177, v178
	v_mul_f32_e32 v178, v159, v83
	v_fmac_f32_e32 v178, v158, v82
	v_fmac_f32_e32 v178, v160, v84
	v_fmac_f32_e32 v178, v161, v85
	v_add_f32_e32 v177, v177, v178
	v_mul_f32_e32 v178, v147, v79
	v_fmac_f32_e32 v178, v146, v78
	v_mul_f32_e32 v179, v155, v75
	v_fmac_f32_e32 v178, v148, v80
	v_fmac_f32_e32 v179, v154, v74
	v_fmac_f32_e32 v178, v149, v81
	v_fmac_f32_e32 v179, v156, v76
	v_add_f32_e32 v178, 0, v178
	v_fmac_f32_e32 v179, v157, v77
	v_add_f32_e32 v178, v178, v179
	v_mul_f32_e32 v179, v151, v71
	v_fmac_f32_e32 v179, v150, v70
	v_fmac_f32_e32 v179, v152, v72
	v_fmac_f32_e32 v179, v153, v73
	v_add_f32_e32 v178, v178, v179
	v_mul_f32_e32 v179, v159, v67
	v_fmac_f32_e32 v179, v158, v66
	v_fmac_f32_e32 v179, v160, v68
	v_fmac_f32_e32 v179, v161, v69
	v_add_f32_e32 v178, v178, v179
	v_mul_f32_e32 v179, v147, v63
	v_fmac_f32_e32 v179, v146, v62
	v_mul_f32_e32 v180, v155, v59
	v_fmac_f32_e32 v179, v148, v64
	v_fmac_f32_e32 v180, v154, v58
	v_fmac_f32_e32 v179, v149, v65
	v_fmac_f32_e32 v180, v156, v60
	v_add_f32_e32 v179, 0, v179
	v_fmac_f32_e32 v180, v157, v61
	v_add_f32_e32 v179, v179, v180
	v_mul_f32_e32 v180, v151, v55
	v_fmac_f32_e32 v180, v150, v54
	v_fmac_f32_e32 v180, v152, v56
	v_fmac_f32_e32 v180, v153, v57
	v_add_f32_e32 v179, v179, v180
	v_mul_f32_e32 v180, v159, v51
	v_fmac_f32_e32 v180, v158, v50
	v_fmac_f32_e32 v180, v160, v52
	v_fmac_f32_e32 v180, v161, v53
	v_add_f32_e32 v179, v179, v180
	v_mul_f32_e32 v180, v147, v47
	v_fmac_f32_e32 v180, v146, v46
	v_mul_f32_e32 v181, v155, v43
	v_fmac_f32_e32 v180, v148, v48
	v_fmac_f32_e32 v181, v154, v42
	v_fmac_f32_e32 v180, v149, v49
	v_fmac_f32_e32 v181, v156, v44
; #define GAS __attribute__((address_space(1)))
; __device__ __forceinline__ unsigned pk2(float lo, float hi) { const f32x2_t v = {lo, hi}; return __builtin_bit_cast(unsigned, __builtin_convertvector(v, bf16x2_t)); }
; __global__ void __launch_bounds__(NWAVES * 64, 2) fwd(Args args) {
;     ...
;             GAS v4u* o16 = (GAS v4u*)(XB + (size_t)m * D) + lane;
; #pragma unroll
;             for (int jj = 0; jj < 2; ++jj) { v4u o; o.x = pk2(v[2 * jj].x, v[2 * jj].y); o.y = pk2(v[2 * jj].z, v[2 * jj].w); o.z = pk2(v[2 * jj + 1].x, v[2 * jj + 1].y); o.w = pk2(v[2 * jj + 1].z, v[2 * jj + 1].w); o16[64 * jj] = o; }
;             float acc[8];
; #pragma unroll
;             for (int c = 0; c < 8; ++c) { float a = 0.f;
; #pragma unroll
;                 for (int j = 0; j < 4; ++j) { const f32x4 w = wreg[c][j]; a += v[j].x * w.x + v[j].y * w.y + v[j].z * w.z + v[j].w * w.w; }
;                 acc[c] = a; }
;             float a4[4], a2[2], a1;
;             { const bool hi = (lane & 32) != 0;
; #pragma unroll
;               for (int i = 0; i < 4; ++i) { const float send = hi ? acc[i] : acc[4 + i], keep = hi ? acc[4 + i] : acc[i]; a4[i] = keep + __shfl_xor(send, 32); } }
;             { const bool hi = (lane & 16) != 0;
; #pragma unroll
;               for (int i = 0; i < 2; ++i) { const float send = hi ? a4[i] : a4[2 + i], keep = hi ? a4[2 + i] : a4[i]; a2[i] = keep + __shfl_xor(send, 16); } }
;             { const bool hi = (lane & 8) != 0; const float send = hi ? a2[0] : a2[1], keep = hi ? a2[1] : a2[0]; a1 = keep + __shfl_xor(send, 8); }
;             a1 += __shfl_xor(a1, 4); a1 += __shfl_xor(a1, 2); a1 += __shfl_xor(a1, 1);
;             if ((lane & 7) == 0) { const int cc = lane >> 3; float r;
;                 if (cc < 4) r = 1.f / (1.f + expf(-a1));
;                 else { const int h = cc - 4; const float z = a1 + dt_bias[h]; const float sp = z > 20.f ? z : log1pf(expf(z)); r = -expf(A_log[h]) * sp; }
	v_add_f32_e32 v180, 0, v180
	v_fmac_f32_e32 v181, v157, v45
	v_add_f32_e32 v180, v180, v181
	v_mul_f32_e32 v181, v151, v39
	v_fmac_f32_e32 v181, v150, v38
	v_fmac_f32_e32 v181, v152, v40
	v_fmac_f32_e32 v181, v153, v41
	v_add_f32_e32 v180, v180, v181
	v_mul_f32_e32 v181, v159, v35
	v_fmac_f32_e32 v181, v158, v34
	v_fmac_f32_e32 v181, v160, v36
	v_fmac_f32_e32 v181, v161, v37
	v_add_f32_e32 v180, v180, v181
	v_mul_f32_e32 v181, v147, v31
	v_fmac_f32_e32 v181, v146, v30
	v_mul_f32_e32 v182, v155, v27
	v_fmac_f32_e32 v181, v148, v32
	v_fmac_f32_e32 v182, v154, v26
	v_fmac_f32_e32 v181, v149, v33
	v_fmac_f32_e32 v182, v156, v28
	v_add_f32_e32 v181, 0, v181
	v_fmac_f32_e32 v182, v157, v29
	v_add_f32_e32 v181, v181, v182
	v_mul_f32_e32 v182, v151, v23
	v_fmac_f32_e32 v182, v150, v22
	v_fmac_f32_e32 v182, v152, v24
	v_fmac_f32_e32 v182, v153, v25
	v_add_f32_e32 v181, v181, v182
	v_mul_f32_e32 v182, v159, v19
	v_fmac_f32_e32 v182, v158, v18
	v_fmac_f32_e32 v182, v160, v20
	v_fmac_f32_e32 v182, v161, v21
	v_add_f32_e32 v181, v181, v182
	v_mul_f32_e32 v182, v147, v15
	v_fmac_f32_e32 v182, v146, v14
	v_mul_f32_e32 v183, v155, v11
	v_fmac_f32_e32 v182, v148, v16
	v_fmac_f32_e32 v183, v154, v10
	v_fmac_f32_e32 v182, v149, v17
	v_fmac_f32_e32 v183, v156, v12
	v_add_f32_e32 v182, 0, v182
	v_fmac_f32_e32 v183, v157, v13
	v_add_f32_e32 v182, v182, v183
	v_mul_f32_e32 v183, v151, v7
	v_fmac_f32_e32 v183, v150, v6
	v_fmac_f32_e32 v183, v152, v8
	v_fmac_f32_e32 v183, v153, v9
	v_and_b32_e32 v186, 64, v1
	v_add_f32_e32 v182, v182, v183
	v_mul_f32_e32 v183, v159, v3
	v_xor_b32_e32 v185, 32, v1
	v_add_u32_e32 v186, 64, v186
	v_fmac_f32_e32 v183, v158, v2
	v_cmp_lt_i32_e32 vcc, v185, v186
	v_fmac_f32_e32 v183, v160, v4
	v_cndmask_b32_e64 v187, v173, v179, s[6:7]
	v_cndmask_b32_e32 v185, v1, v185, vcc
	v_lshlrev_b32_e32 v185, 2, v185
	v_fmac_f32_e32 v183, v161, v5
	v_cndmask_b32_e64 v173, v179, v173, s[6:7]
	v_cndmask_b32_e64 v179, v176, v180, s[6:7]
	v_add_f32_e32 v182, v182, v183
	ds_bpermute_b32 v179, v185, v179
	v_cndmask_b32_e64 v176, v180, v176, s[6:7]
	v_cndmask_b32_e64 v180, v177, v181, s[6:7]
	v_cndmask_b32_e64 v183, v178, v182, s[6:7]
	ds_bpermute_b32 v187, v185, v187
	ds_bpermute_b32 v180, v185, v180
	ds_bpermute_b32 v183, v185, v183
	s_waitcnt lgkmcnt(3)
	v_add_f32_e32 v176, v176, v179
	v_xor_b32_e32 v179, 16, v1
	v_cndmask_b32_e64 v177, v181, v177, s[6:7]
	v_cndmask_b32_e64 v178, v182, v178, s[6:7]
	v_cmp_lt_i32_e32 vcc, v179, v186
	s_waitcnt lgkmcnt(2)
	v_add_f32_e32 v173, v173, v187
	s_waitcnt lgkmcnt(1)
	v_add_f32_e32 v177, v177, v180
	s_waitcnt lgkmcnt(0)
	v_add_f32_e32 v178, v178, v183
	v_cndmask_b32_e32 v179, v1, v179, vcc
	v_lshlrev_b32_e32 v179, 2, v179
	v_cndmask_b32_e64 v180, v173, v177, s[8:9]
	v_cndmask_b32_e64 v181, v176, v178, s[8:9]
	ds_bpermute_b32 v180, v179, v180
	ds_bpermute_b32 v179, v179, v181
	v_cndmask_b32_e64 v176, v178, v176, s[8:9]
	v_xor_b32_e32 v178, 8, v1
	v_cndmask_b32_e64 v173, v177, v173, s[8:9]
	v_cmp_lt_i32_e32 vcc, v178, v186
	s_waitcnt lgkmcnt(1)
	v_add_f32_e32 v173, v173, v180
	s_waitcnt lgkmcnt(0)
	v_add_f32_e32 v176, v176, v179
	v_cndmask_b32_e32 v178, v1, v178, vcc
	v_cndmask_b32_e64 v177, v173, v176, s[10:11]
	v_lshlrev_b32_e32 v178, 2, v178
	ds_bpermute_b32 v177, v178, v177
	v_cndmask_b32_e64 v173, v176, v173, s[10:11]
	v_xor_b32_e32 v176, 4, v1
	v_cmp_lt_i32_e32 vcc, v176, v186
	s_waitcnt lgkmcnt(0)
	v_add_f32_e32 v173, v173, v177
	v_cvt_pk_bf16_f32 v146, v146, v147
	v_cndmask_b32_e32 v176, v1, v176, vcc
	v_lshlrev_b32_e32 v176, 2, v176
	ds_bpermute_b32 v176, v176, v173
	v_cvt_pk_bf16_f32 v147, v148, v149
	v_xor_b32_e32 v148, 2, v1
	v_cmp_lt_i32_e32 vcc, v148, v186
	v_cvt_pk_bf16_f32 v149, v156, v157
	s_waitcnt lgkmcnt(0)
	v_add_f32_e32 v173, v173, v176
	v_cndmask_b32_e32 v148, v1, v148, vcc
	v_lshlrev_b32_e32 v148, 2, v148
	ds_bpermute_b32 v176, v148, v173
	v_cvt_pk_bf16_f32 v148, v154, v155
	global_store_dwordx4 v[170:171], v[146:149], off offset:-1024
	s_nop 1
	v_xor_b32_e32 v147, 1, v1
	v_cmp_lt_i32_e32 vcc, v147, v186
	s_waitcnt lgkmcnt(0)
	v_add_f32_e32 v146, v173, v176
	v_cvt_pk_bf16_f32 v148, v150, v151
	v_cndmask_b32_e32 v147, v1, v147, vcc
	v_lshlrev_b32_e32 v147, 2, v147
	ds_bpermute_b32 v147, v147, v146
	v_cvt_pk_bf16_f32 v149, v152, v153
	v_cvt_pk_bf16_f32 v150, v158, v159
	v_cvt_pk_bf16_f32 v151, v160, v161
	global_store_dwordx4 v[170:171], v[148:151], off
	s_and_saveexec_b64 s[28:29], s[12:13]
	s_cbranch_execz .LrowB_53
	s_waitcnt lgkmcnt(0)
	v_add_f32_e32 v146, v146, v147
	s_and_saveexec_b64 s[44:45], s[14:15]
	s_xor_b64 s[44:45], exec, s[44:45]
	s_cbranch_execz .LrowB_62
	v_add_f32_e32 v146, v146, v241
	v_cmp_nlt_f32_e32 vcc, s3, v146
	s_and_saveexec_b64 s[46:47], vcc
	s_cbranch_execz .LrowB_61
; __global__ void __launch_bounds__(NWAVES * 64, 2) fwd(Args args) {
;     ...
;                 else { const int h = cc - 4; const float z = a1 + dt_bias[h]; const float sp = z > 20.f ? z : log1pf(expf(z)); r = -expf(A_log[h]) * sp; }
	v_mul_f32_e32 v147, 0x3fb8aa3b, v146
	v_rndne_f32_e32 v148, v147
	v_sub_f32_e32 v149, v147, v148
	v_fma_f32 v147, v146, s4, -v147
	v_fmac_f32_e32 v147, 0x32a5705f, v146
	v_add_f32_e32 v147, v149, v147
	v_cvt_i32_f32_e32 v148, v148
	v_exp_f32_e32 v147, v147
	v_cmp_ngt_f32_e32 vcc, s33, v146
	v_ldexp_f32 v147, v147, v148
	s_nop 0
	v_cndmask_b32_e32 v147, 0, v147, vcc
	v_cmp_nlt_f32_e32 vcc, s35, v146
	s_nop 1
	v_cndmask_b32_e32 v160, v175, v147, vcc
	v_add_f32_e32 v148, 1.0, v160
	v_add_f32_e32 v146, -1.0, v148
	v_sub_f32_e32 v147, v146, v148
	v_add_f32_e32 v147, 1.0, v147
	v_sub_f32_e32 v146, v160, v146
	v_add_f32_e32 v149, v146, v147
	v_frexp_mant_f32_e32 v150, v148
	v_cvt_f64_f32_e32 v[146:147], v148
	v_frexp_exp_i32_f64_e32 v146, v[146:147]
	v_cmp_gt_f32_e32 vcc, s37, v150
	s_nop 1
	v_subbrev_co_u32_e32 v154, vcc, 0, v146, vcc
	v_sub_u32_e32 v146, 0, v154
	v_ldexp_f32 v147, v148, v146
	v_add_f32_e32 v148, -1.0, v147
	v_add_f32_e32 v150, 1.0, v147
	v_ldexp_f32 v146, v149, v146
	v_add_f32_e32 v149, 1.0, v148
	v_add_f32_e32 v151, -1.0, v150
	v_sub_f32_e32 v149, v147, v149
	v_sub_f32_e32 v147, v147, v151
	v_add_f32_e32 v149, v146, v149
	v_add_f32_e32 v146, v146, v147
	v_add_f32_e32 v155, v150, v146
	v_rcp_f32_e32 v157, v155
	v_sub_f32_e32 v147, v150, v155
	v_add_f32_e32 v156, v146, v147
	v_add_f32_e32 v147, v148, v149
	v_mul_f32_e32 v159, v147, v157
	v_sub_f32_e32 v146, v148, v147
	v_mul_f32_e32 v148, v155, v159
	v_fma_f32 v150, v159, v155, -v148
	v_fmac_f32_e32 v150, v159, v156
	v_add_f32_e32 v158, v149, v146
	v_add_f32_e32 v146, v148, v150
	v_sub_f32_e32 v149, v147, v146
	v_pk_add_f32 v[152:153], v[146:147], v[148:149] neg_lo:[0,1] neg_hi:[0,1]
	v_mov_b32_e32 v151, v146
	v_pk_add_f32 v[146:147], v[152:153], v[150:151] neg_lo:[0,1] neg_hi:[0,1]
	v_cmp_neq_f32_e32 vcc, s36, v160
	v_add_f32_e32 v147, v158, v147
	v_add_f32_e32 v146, v146, v147
	v_add_f32_e32 v147, v149, v146
	v_mul_f32_e32 v158, v157, v147
	v_mul_f32_e32 v148, v155, v158
	v_fma_f32 v150, v158, v155, -v148
	v_fmac_f32_e32 v150, v158, v156
	v_sub_f32_e32 v149, v149, v147
	v_add_f32_e32 v155, v146, v149
	v_add_f32_e32 v146, v148, v150
	v_sub_f32_e32 v149, v147, v146
	v_pk_add_f32 v[152:153], v[146:147], v[148:149] neg_lo:[0,1] neg_hi:[0,1]
	v_mov_b32_e32 v151, v146
	v_pk_add_f32 v[146:147], v[152:153], v[150:151] neg_lo:[0,1] neg_hi:[0,1]
	s_nop 0
	v_add_f32_e32 v147, v155, v147
	v_add_f32_e32 v146, v146, v147
	v_add_f32_e32 v147, v159, v158
	v_add_f32_e32 v146, v149, v146
	v_sub_f32_e32 v148, v147, v159
	v_mul_f32_e32 v146, v157, v146
	v_sub_f32_e32 v148, v158, v148
	v_add_f32_e32 v148, v148, v146
	v_add_f32_e32 v150, v147, v148
	v_mul_f32_e32 v151, v150, v150
	v_fmamk_f32 v146, v151, 0x3e9b6dac, v174
	v_fmaak_f32 v173, v151, v146, 0x3f2aaada
	v_cvt_f32_i32_e32 v146, v154
	v_sub_f32_e32 v147, v150, v147
	v_sub_f32_e32 v147, v148, v147
	v_ldexp_f32 v152, v147, 1
	v_mul_f32_e32 v147, v150, v151
	v_ldexp_f32 v149, v150, 1
	v_pk_mul_f32 v[150:151], v[146:147], v[172:173]
	s_nop 0
	v_fma_f32 v148, v146, s43, -v150
	v_fmac_f32_e32 v148, 0xb102e308, v146
	v_pk_add_f32 v[146:147], v[150:151], v[148:149]
	s_nop 0
	v_sub_f32_e32 v149, v147, v149
	v_sub_f32_e32 v149, v151, v149
	v_add_f32_e32 v153, v152, v149
	v_mov_b32_e32 v152, v150
	v_pk_add_f32 v[150:151], v[146:147], v[150:151] neg_lo:[0,1] neg_hi:[0,1]
	v_pk_add_f32 v[154:155], v[146:147], v[152:153]
	v_mov_b32_e32 v149, v146
	v_mov_b32_e32 v151, v155
	v_pk_add_f32 v[156:157], v[148:149], v[150:151] neg_lo:[0,1] neg_hi:[0,1]
	v_pk_add_f32 v[148:149], v[148:149], v[150:151]
	v_mov_b32_e32 v152, v153
	v_pk_add_f32 v[150:151], v[148:149], v[146:147] op_sel:[1,0] op_sel_hi:[0,1] neg_lo:[0,1] neg_hi:[0,1]
	v_pk_add_f32 v[158:159], v[154:155], v[150:151] op_sel_hi:[1,0] neg_lo:[0,1] neg_hi:[0,1]
	v_mov_b32_e32 v154, v155
	v_mov_b32_e32 v155, v149
	v_pk_mov_b32 v[150:151], v[146:147], v[150:151] op_sel:[1,0]
	v_mov_b32_e32 v153, v146
	v_pk_add_f32 v[150:151], v[154:155], v[150:151] neg_lo:[0,1] neg_hi:[0,1]
	v_mov_b32_e32 v158, v156
	v_pk_add_f32 v[146:147], v[152:153], v[150:151] neg_lo:[0,1] neg_hi:[0,1]
	v_mov_b32_e32 v157, v149
	v_pk_add_f32 v[150:151], v[158:159], v[146:147]
	s_nop 0
	v_pk_add_f32 v[152:153], v[150:151], v[150:151] op_sel:[0,1] op_sel_hi:[1,0]
	s_nop 0
	v_pk_add_f32 v[148:149], v[148:149], v[152:153] op_sel:[1,0] op_sel_hi:[0,1]
	v_mov_b32_e32 v151, v148
	v_pk_add_f32 v[154:155], v[150:151], v[156:157] neg_lo:[0,1] neg_hi:[0,1]
	v_mov_b32_e32 v147, v152
	v_sub_f32_e32 v149, v150, v154
	v_pk_add_f32 v[146:147], v[146:147], v[154:155] neg_lo:[0,1] neg_hi:[0,1]
	v_sub_f32_e32 v149, v156, v149
	v_add_f32_e32 v146, v146, v149
	v_add_f32_e32 v146, v146, v147
	v_add_f32_e32 v146, v148, v146
	v_cndmask_b32_e32 v146, v175, v146, vcc
	v_cmp_lt_f32_e64 vcc, |v160|, s48
	s_nop 1
	v_cndmask_b32_e32 v146, v146, v160, vcc

; __global__ void __launch_bounds__(NWAVES * 64, 2) fwd(Args args) {
;     ...
;         for (int m = gw; m < M; m += NGW) {
;             f32x4 v[4];
; #pragma unroll
;             for (int j = 0; j < 4; ++j) v[j] = vn[j];
;     ...
;                 if (cc < 4) r = 1.f / (1.f + expf(-a1));
;                 else { const int h = cc - 4; const float z = a1 + dt_bias[h]; const float sp = z > 20.f ? z : log1pf(expf(z)); r = -expf(A_log[h]) * sp; }
;                 GBT[(size_t)m * 8 + cc] = r;
.LrowB_62:
	s_andn2_saveexec_b64 s[44:45], s[44:45]
	s_cbranch_execz .LrowB_52
	v_mul_f32_e32 v147, 0xbfb8aa3b, v146
	v_rndne_f32_e32 v148, v147
	v_sub_f32_e32 v149, v147, v148
	v_fma_f32 v147, v146, s49, -v147
	v_fmac_f32_e32 v147, 0xb2a5705f, v146
	v_add_f32_e32 v147, v149, v147
	v_cvt_i32_f32_e32 v148, v148
	v_exp_f32_e32 v147, v147
	v_cmp_nlt_f32_e32 vcc, s50, v146
	v_ldexp_f32 v147, v147, v148
	s_nop 0
	v_cndmask_b32_e32 v147, 0, v147, vcc
	v_cmp_ngt_f32_e32 vcc, s51, v146
	s_nop 1
	v_cndmask_b32_e32 v146, v175, v147, vcc
	v_add_f32_e32 v146, 1.0, v146
	v_div_scale_f32 v147, s[46:47], v146, v146, 1.0
	v_rcp_f32_e32 v148, v147
	s_nop 0
	v_fma_f32 v149, -v147, v148, 1.0
	v_fmac_f32_e32 v148, v149, v148
	v_div_scale_f32 v149, vcc, 1.0, v146, 1.0
	v_mul_f32_e32 v150, v149, v148
	v_fma_f32 v151, -v147, v150, v149
	v_fmac_f32_e32 v150, v151, v148
	v_fma_f32 v147, -v147, v150, v149
	v_div_fmas_f32 v147, v147, v148, v150
	v_div_fixup_f32 v147, v147, v146, 1.0
	s_branch .LrowB_52
.LrowB_52:
	s_or_b64 exec, exec, s[44:45]
	global_store_dword v[168:169], v147, off
.LrowB_53:
	s_or_b64 exec, exec, s[28:29]
	v_lshl_add_u64 v[168:169], v[168:169], 0, s[16:17]
	v_lshl_add_u64 v[170:171], v[170:171], 0, s[20:21]
	s_waitcnt vmcnt(7) lgkmcnt(0)
	v_mov_b32_e32 v146, v130
	v_mov_b32_e32 v147, v131
	v_mov_b32_e32 v148, v132
	v_mov_b32_e32 v149, v133
	v_mov_b32_e32 v154, v134
	v_mov_b32_e32 v155, v135
	v_mov_b32_e32 v156, v136
	v_mov_b32_e32 v157, v137
	v_mov_b32_e32 v150, v138
	v_mov_b32_e32 v151, v139
	v_mov_b32_e32 v152, v140
	v_mov_b32_e32 v153, v141
	v_mov_b32_e32 v158, v142
	v_mov_b32_e32 v159, v143
	v_mov_b32_e32 v160, v144
	v_mov_b32_e32 v161, v145
	s_sub_u32 s98, s98, 1
	s_cmp_lg_u32 s98, 0
	s_cbranch_scc1 .LrowA_top
